# in-proj: the 32 tiles of the fifth round are spread over all 8 XCDs (4 blocks each) instead of all on one
# baseline (speedup 1.0000x reference)
.LBB0_1298:
	s_or_b64 exec, exec, s[0:1]
	s_add_i32 s20, s12, s89
	s_add_i32 s62, s62, s63
	s_cmpk_lg_i32 s89, 0x100
	s_cbranch_scc1 .Lip_keep
	s_cmpk_ge_i32 s12, 0x400
	s_cbranch_scc1 .LBB0_1680
	s_cmpk_lt_i32 s20, 0x400
	s_cbranch_scc1 .Lip_keep
	v_readlane_b32 s0, v255, 22
	s_and_b32 s1, s0, 31
	s_cmpk_lt_i32 s1, 4
	s_cbranch_scc0 .LBB0_1680
	s_lshr_b32 s0, s0, 5
	s_lshl_b32 s1, s1, 3
	s_add_i32 s0, s0, s1
	s_add_i32 s20, s0, 0x400
	s_lshl_b32 s62, s20, 8
.Lip_keep:
	s_cmpk_gt_i32 s20, 0x41f
	s_cbranch_scc1 .LBB0_1680
